# FFN-out sample-path sgemm unit K-split four ways (owner + 3 conversion-free partner workgroups), both variants
# speedup vs baseline: 1.0151x; 1.0016x over previous
.LBB0_2746:
	s_and_b64 vcc, exec, s[2:3]
	s_cbranch_vccz .LBB0_2881
	v_lshlrev_b32_e32 v0, 4, v56
	v_add_u32_e32 v1, 0x2000, v0
	v_ashrrev_i32_e32 v2, 31, v1
	v_lshrrev_b32_e32 v2, 22, v2
	v_add_u32_e32 v2, v1, v2
	v_ashrrev_i32_e32 v71, 10, v2
	v_mul_i32_i24_e32 v2, 0x400, v71
	v_sub_u32_e32 v1, v1, v2
	v_lshrrev_b32_e32 v2, 4, v1
	v_bitop3_b32 v1, v2, v1, 32 bitop3:0x6c
	v_ashrrev_i32_e32 v2, 31, v1
	v_lshrrev_b32_e32 v2, 26, v2
	v_add_u32_e32 v2, v1, v2
	v_lshlrev_b32_e32 v3, 3, v71
	v_ashrrev_i32_e32 v72, 6, v2
	v_and_b32_e32 v3, -16, v3
	v_add_u32_e32 v3, v72, v3
	v_and_b32_e32 v4, 3, v72
	s_mov_b32 s3, 0xffffe0
	v_lshrrev_b32_e32 v5, 2, v3
	v_lshlrev_b32_e32 v6, 1, v3
	v_and_b32_e32 v2, 0xc0, v2
	v_writelane_b32 v255, s40, 10
	v_and_or_b32 v4, v3, s3, v4
	v_and_b32_e32 v5, 4, v5
	v_and_b32_e32 v6, 24, v6
	v_sub_u32_e32 v1, v1, v2
	v_readlane_b32 s2, v255, 7
	v_or3_b32 v4, v4, v5, v6
	v_lshlrev_b32_e32 v5, 5, v71
	v_ashrrev_i16_sdwa v1, v215, sext(v1) dst_sel:DWORD dst_unused:UNUSED_PAD src0_sel:DWORD src1_sel:BYTE_0
	s_ashr_i32 s95, s2, 6
	v_and_b32_e32 v73, 32, v5
	v_bfe_i32 v74, v1, 0, 16
	s_movk_i32 s2, 0xb00
	v_mul_u32_u24_e32 v4, 0xb00, v4
	v_add_u32_e32 v1, v73, v74
	v_mul_lo_u32 v2, v3, s2
	v_add_lshl_u32 v170, v4, v1, 1
	v_add_lshl_u32 v172, v1, v2, 1
	v_bfe_i32 v1, v56, 27, 1
	v_lshrrev_b32_e32 v1, 22, v1
	v_add_u32_e32 v1, v0, v1
	v_and_b32_e32 v1, 0xfffffc00, v1
	v_sub_u32_e32 v0, v0, v1
	v_lshrrev_b32_e32 v1, 4, v0
	v_ashrrev_i32_e32 v2, 31, v56
	v_bitop3_b32 v0, v1, v0, 32 bitop3:0x6c
	v_lshrrev_b32_e32 v2, 26, v2
	v_ashrrev_i32_e32 v1, 31, v0
	v_add_u32_e32 v2, v56, v2
	v_lshrrev_b32_e32 v1, 26, v1
	v_ashrrev_i32_e32 v76, 6, v2
	v_add_u32_e32 v1, v0, v1
	v_lshlrev_b32_e32 v2, 3, v76
	v_ashrrev_i32_e32 v75, 6, v1
	v_and_b32_e32 v2, -16, v2
	v_add_u32_e32 v2, v75, v2
	v_and_b32_e32 v3, 3, v75
	v_lshrrev_b32_e32 v4, 2, v2
	v_lshlrev_b32_e32 v5, 1, v2
	v_and_b32_e32 v1, 0xc0, v1
	v_and_or_b32 v3, v2, s3, v3
	v_and_b32_e32 v4, 4, v4
	v_and_b32_e32 v5, 24, v5
	v_sub_u32_e32 v0, v0, v1
	s_lshl_b32 s17, s95, 10
	v_or3_b32 v3, v3, v4, v5
	v_lshlrev_b32_e32 v4, 5, v76
	v_ashrrev_i16_sdwa v0, v215, sext(v0) dst_sel:DWORD dst_unused:UNUSED_PAD src0_sel:DWORD src1_sel:BYTE_0
	v_mul_lo_u32 v1, v2, s2
	v_readlane_b32 s2, v254, 19
	v_and_b32_e32 v77, 32, v4
	v_bfe_i32 v78, v0, 0, 16
	s_add_u32 s60, s77, s2
	v_readlane_b32 s2, v254, 17
	v_mul_u32_u24_e32 v3, 0xb00, v3
	v_add_u32_e32 v0, v77, v78
	s_addc_u32 s61, s78, s2
	s_add_i32 s30, s17, 0
	v_add_lshl_u32 v174, v3, v0, 1
	s_add_i32 m0, s30, 0x10000
	v_add_lshl_u32 v176, v0, v1, 1
	global_load_lds_dwordx4 v174, s[60:61]
	s_add_i32 m0, s30, 0x12000
	s_add_u32 s2, s60, 0xb0000
	global_load_lds_dwordx4 v170, s[60:61]
	s_addc_u32 s3, s61, 0
	s_add_i32 m0, s30, 0x14000
	v_writelane_b32 v255, s37, 14
	global_load_lds_dwordx4 v174, s[2:3]
	s_add_i32 m0, s30, 0x16000
	s_nop 0
	global_load_lds_dwordx4 v170, s[2:3]
	v_readlane_b32 s2, v254, 16
	s_add_u32 s58, s75, s2
	v_readlane_b32 s2, v254, 13
	s_addc_u32 s59, s76, s2
	s_add_i32 s31, s30, 0x2000
	s_mov_b32 m0, s30
	s_add_u32 s2, s58, 0xb0000
	global_load_lds_dwordx4 v176, s[58:59]
	s_mov_b32 m0, s31
	s_addc_u32 s3, s59, 0
	s_add_i32 s79, s30, 0x4000
	global_load_lds_dwordx4 v172, s[58:59]
	s_mov_b32 m0, s79
	s_add_i32 s80, s30, 0x6000
	global_load_lds_dwordx4 v176, s[2:3]
	s_mov_b32 m0, s80
	s_abs_i32 s8, s74
	global_load_lds_dwordx4 v172, s[2:3]
	v_cvt_f32_u32_e32 v0, s8
	s_sub_i32 s20, 0, s8
	s_abs_i32 s3, s37
	s_ashr_i32 s2, s37, 31
	v_rcp_iflag_f32_e32 v0, v0
	s_nop 0
	v_mul_f32_e32 v0, 0x4f7ffffe, v0
	v_cvt_u32_f32_e32 v0, v0
	s_nop 0
	v_readfirstlane_b32 s28, v0
	s_mul_i32 s20, s20, s28
	s_mul_hi_u32 s20, s28, s20
	s_add_i32 s28, s28, s20
	s_mul_hi_u32 s20, s3, s28
	s_mul_i32 s20, s20, s8
	s_sub_i32 s3, s3, s20
	s_sub_i32 s20, s3, s8
	s_cmp_ge_u32 s3, s8
	s_cselect_b32 s3, s20, s3
	s_sub_i32 s20, s3, s8
	s_cmp_ge_u32 s3, s8
	s_cselect_b32 s3, s20, s3
	s_xor_b32 s3, s3, s2
	s_sub_i32 s29, s3, s2
	s_mov_b32 s100, 0
	s_mov_b32 s101, 0
	s_cmp_gt_i32 s29, 31
	s_cbranch_scc0 .LBB0_2755
	s_cmpk_lt_i32 s29, 0xa0
	s_cbranch_scc1 .LBB0_2748
	s_sub_i32 s101, s29, 0xa0
	s_lshr_b32 s101, s101, 5
	s_add_i32 s101, s101, 1
	s_mul_i32 s100, s101, 0xc0
	s_cmp_eq_u32 s101, 3
	s_cselect_b32 s101, 32, 0
	s_sub_i32 s100, s100, s101
	s_mov_b32 s101, 0
	s_and_b32 s29, s29, 31
	s_branch .LBB0_2755

.LBB0_2755:
	v_lshl_add_u64 v[248:249], v[162:163], 0, s[100:101]
	v_lshl_or_b32 v24, s29, 5, v201
	s_movk_i32 s2, 0x1600
	v_mad_i64_i32 v[30:31], s[2:3], v24, s2, v[164:165]
	v_lshl_add_u64 v[30:31], v[30:31], 0, s[100:101]
	global_load_dwordx4 v[48:51], v[248:249], off
	global_load_dwordx4 v[52:55], v[30:31], off
	global_load_dwordx4 v[80:83], v[248:249], off offset:32
	global_load_dwordx4 v[84:87], v[30:31], off offset:32
	global_load_dwordx4 v[88:91], v[248:249], off offset:64
	global_load_dwordx4 v[92:95], v[30:31], off offset:64
	global_load_dwordx4 v[96:99], v[248:249], off offset:96
	global_load_dwordx4 v[100:103], v[30:31], off offset:96
	global_load_dwordx4 v[104:107], v[248:249], off offset:128
	global_load_dwordx4 v[108:111], v[30:31], off offset:128
	global_load_dwordx4 v[112:115], v[248:249], off offset:160
	global_load_dwordx4 v[116:119], v[30:31], off offset:160
	v_add_u32_e32 v30, 0x8c00, v204
	v_add_u32_e32 v26, v24, v202
	v_add_u32_e32 v28, 0x4000, v26
	v_ashrrev_i32_e32 v27, 31, v26
	v_ashrrev_i32_e32 v29, 31, v28
	v_lshl_add_u64 v[26:27], v[26:27], 2, s[92:93]
	v_lshl_add_u64 v[28:29], v[28:29], 2, s[92:93]
	global_load_dword v26, v[26:27], off
	s_nop 0
	global_load_dword v25, v[28:29], off
	v_add_u32_e32 v27, 0x8000, v204
	v_add_u32_e32 v28, 0x8400, v204
	v_add_u32_e32 v29, 0x8800, v204
	s_waitcnt vmcnt(12)
	v_mfma_f32_32x32x16_bf16 v[0:15], v[48:51], v[52:55], 0
	s_waitcnt vmcnt(10)
	v_mfma_f32_32x32x16_bf16 v[0:15], v[80:83], v[84:87], v[0:15]
	s_waitcnt vmcnt(8)
	v_mfma_f32_32x32x16_bf16 v[0:15], v[88:91], v[92:95], v[0:15]
	s_waitcnt vmcnt(6)
	v_mfma_f32_32x32x16_bf16 v[0:15], v[96:99], v[100:103], v[0:15]
	s_waitcnt vmcnt(4)
	v_mfma_f32_32x32x16_bf16 v[0:15], v[104:107], v[108:111], v[0:15]
	s_cmp_lt_u32 s100, 0x180
	s_cbranch_scc0 .Lsp_s6
	s_waitcnt vmcnt(2)
	v_mfma_f32_32x32x16_bf16 v[0:15], v[112:115], v[116:119], v[0:15]
.Lsp_s6:
	s_waitcnt vmcnt(0)
	s_nop 11
	ds_write2_b32 v27, v0, v1 offset1:32
	ds_write2_b32 v27, v2, v3 offset0:64 offset1:96
	ds_write2_b32 v28, v4, v5 offset1:32
	ds_write2_b32 v28, v6, v7 offset0:64 offset1:96
	ds_write2_b32 v29, v8, v9 offset1:32
	ds_write2_b32 v29, v10, v11 offset0:64 offset1:96
	ds_write2_b32 v30, v12, v13 offset1:32
	ds_write2_b32 v30, v14, v15 offset0:64 offset1:96
	s_waitcnt lgkmcnt(0)
	s_barrier
	s_and_saveexec_b64 s[38:39], s[34:35]
	s_movk_i32 s20, 0x1ff
	s_movk_i32 s36, 0x1080
	s_cbranch_execz .LBB0_2758
	s_mov_b64 s[2:3], 0
	v_mov_b32_e32 v0, v200

.LBB0_2758:
	s_or_b64 exec, exec, s[38:39]
	s_waitcnt lgkmcnt(0)
	s_barrier
	s_sub_u32 s38, s92, 0x24ac0000
	s_subb_u32 s39, s93, 0
	v_lshlrev_b32_e32 v34, 4, v200
	v_mov_b32_e32 v35, s29
	v_mul_u32_u24_e32 v35, 0x6000, v35
	v_add_u32_e32 v34, v34, v35
	v_mov_b32_e32 v35, 0
	v_lshl_add_u64 v[34:35], v[34:35], 0, s[38:39]
	v_readlane_b32 s38, v254, 49
	s_nop 3
	s_add_i32 s38, s38, 1
	s_cmp_lg_u32 s100, 0
	s_cbranch_scc1 .Lsp_hi
	v_add_co_u32_e32 v36, vcc, 0x2000, v34
	v_addc_co_u32_e32 v37, vcc, 0, v35, vcc
	v_add_co_u32_e32 v38, vcc, 0x4000, v34
	v_addc_co_u32_e32 v39, vcc, 0, v35, vcc
	s_mov_b32 s39, 0
.Lsp_poll:
	global_load_dwordx2 v[40:41], v[34:35], off sc1
	global_load_dwordx2 v[42:43], v[34:35], off offset:8 sc1
	global_load_dwordx2 v[44:45], v[36:37], off sc1
	global_load_dwordx2 v[46:47], v[36:37], off offset:8 sc1
	global_load_dwordx2 v[16:17], v[38:39], off sc1
	global_load_dwordx2 v[18:19], v[38:39], off offset:8 sc1
	s_waitcnt vmcnt(0)
	v_cmp_ne_u32_e32 vcc, s38, v41
	v_cmp_ne_u32_e64 s[2:3], s38, v43
	s_or_b64 vcc, vcc, s[2:3]
	v_cmp_ne_u32_e64 s[2:3], s38, v45
	s_or_b64 vcc, vcc, s[2:3]
	v_cmp_ne_u32_e64 s[2:3], s38, v47
	s_or_b64 vcc, vcc, s[2:3]
	v_cmp_ne_u32_e64 s[2:3], s38, v17
	s_or_b64 vcc, vcc, s[2:3]
	v_cmp_ne_u32_e64 s[2:3], s38, v19
	s_or_b64 vcc, vcc, s[2:3]
	s_cbranch_vccz .Lsp_got
	s_add_i32 s39, s39, 1
	s_cmp_lt_u32 s39, 0x4000
	s_cbranch_scc0 .Lsp_got
	s_sleep 2
	s_branch .Lsp_poll
.Lsp_got:
	ds_read_b32 v0, v205
	s_waitcnt vmcnt(1) lgkmcnt(0)
	v_add_f32_e32 v0, v0, v40
	v_add_f32_e32 v0, v0, v44
	v_add_f32_e32 v0, v0, v16
	v_add_f32_e32 v4, v26, v0
	v_add_u32_e32 v0, v24, v206
	v_ashrrev_i32_e32 v1, 31, v0
	v_lshl_add_u64 v[2:3], v[0:1], 2, s[92:93]
	v_lshl_add_u64 v[0:1], v[0:1], 1, s[56:57]
	global_store_dword v[2:3], v4, off
	v_cvt_pk_bf16_f32 v2, v4, v33
	global_store_short v[0:1], v2, off
	v_and_b32_e32 v0, 64, v216
	v_add_u32_e32 v6, 64, v0
	v_xor_b32_e32 v0, 1, v216
	v_cmp_lt_i32_e32 vcc, v0, v6
	v_mul_f32_e32 v1, v4, v4
	s_nop 0
	v_cndmask_b32_e32 v0, v216, v0, vcc
	v_lshlrev_b32_e32 v0, 2, v0
	ds_bpermute_b32 v2, v0, v1
	v_xor_b32_e32 v1, 2, v216
	v_cmp_lt_i32_e32 vcc, v1, v6
	s_waitcnt lgkmcnt(0)
	v_fmac_f32_e32 v2, v4, v4
	v_cndmask_b32_e32 v1, v216, v1, vcc
	v_lshlrev_b32_e32 v1, 2, v1
	s_waitcnt lgkmcnt(0)
	s_nop 1
	v_add_f32_dpp v3, v2, v2 quad_perm:[2,3,0,1] row_mask:0xf bank_mask:0xf
	v_xor_b32_e32 v2, 4, v216
	v_cmp_lt_i32_e32 vcc, v2, v6
	s_nop 1
	v_cndmask_b32_e32 v2, v216, v2, vcc
	v_lshlrev_b32_e32 v2, 2, v2
	s_waitcnt lgkmcnt(0)
	s_nop 1
	v_add_f32_dpp v4, v3, v3 row_half_mirror row_mask:0xf bank_mask:0xf
	v_xor_b32_e32 v3, 8, v216
	v_cmp_lt_i32_e32 vcc, v3, v6
	s_nop 1
	v_cndmask_b32_e32 v3, v216, v3, vcc
	v_lshlrev_b32_e32 v3, 2, v3
	s_waitcnt lgkmcnt(0)
	s_nop 1
	v_add_f32_dpp v5, v4, v4 row_mirror row_mask:0xf bank_mask:0xf
	v_xor_b32_e32 v4, 16, v216
	v_cmp_lt_i32_e32 vcc, v4, v6
	s_nop 1
	v_cndmask_b32_e32 v4, v216, v4, vcc
	v_lshlrev_b32_e32 v4, 2, v4
	v_mov_b32_e32 v6, v5
	s_nop 1
	v_permlane16_swap_b32_e32 v6, v5
	s_and_saveexec_b64 s[2:3], s[90:91]
	s_cbranch_execz .LBB0_2760
	s_waitcnt lgkmcnt(0)
	v_add_f32_e32 v5, v5, v6
	v_mul_f32_e32 v5, 0x4b800000, v5
	v_trunc_f32_e32 v5, v5
	v_mul_f32_e32 v6, 0x2f800000, v5
	v_floor_f32_e32 v7, v6
	v_fmac_f32_e32 v5, 0xcf800000, v7
	v_cvt_u32_f32_e32 v6, v5
	v_cvt_u32_f32_e32 v7, v7
	global_atomic_add_x2 v[166:167], v[6:7], off
.LBB0_2760:
	s_or_b64 exec, exec, s[2:3]
	v_add_u32_e32 v5, v70, v208
	ds_read_b32 v5, v5
	s_waitcnt vmcnt(2) lgkmcnt(0)
	v_add_f32_e32 v5, v5, v42
	v_add_f32_e32 v5, v5, v46
	v_add_f32_e32 v5, v5, v18
	v_add_f32_e32 v5, v25, v5
	v_mul_f32_e32 v6, v5, v5
	ds_bpermute_b32 v0, v0, v6
	s_waitcnt lgkmcnt(0)
	v_fmac_f32_e32 v0, v5, v5
	s_waitcnt lgkmcnt(0)
	s_nop 1
	v_add_f32_dpp v0, v0, v0 quad_perm:[2,3,0,1] row_mask:0xf bank_mask:0xf
	v_add_u32_e32 v2, v24, v207
	s_waitcnt lgkmcnt(0)
	s_nop 1
	v_add_f32_dpp v0, v0, v0 row_half_mirror row_mask:0xf bank_mask:0xf
	v_ashrrev_i32_e32 v3, 31, v2
	v_lshl_add_u64 v[6:7], v[2:3], 2, s[92:93]
	v_lshl_add_u64 v[2:3], v[2:3], 1, s[56:57]
	global_store_dword v[6:7], v5, off
	s_waitcnt lgkmcnt(0)
	s_nop 1
	v_add_f32_dpp v0, v0, v0 row_mirror row_mask:0xf bank_mask:0xf
	v_mov_b32_e32 v1, v0
	s_nop 1
	v_permlane16_swap_b32_e32 v1, v0
	v_cvt_pk_bf16_f32 v4, v5, v33
	global_store_short v[2:3], v4, off
	s_and_saveexec_b64 s[2:3], s[90:91]
	s_cbranch_execz .LBB0_2754
	s_waitcnt lgkmcnt(0)
	v_add_f32_e32 v0, v0, v1
	v_mul_f32_e32 v0, 0x4b800000, v0
	v_trunc_f32_e32 v0, v0
	v_mul_f32_e32 v1, 0x2f800000, v0
	v_floor_f32_e32 v1, v1
	v_fmac_f32_e32 v0, 0xcf800000, v1
	v_cvt_u32_f32_e32 v0, v0
	v_cvt_u32_f32_e32 v1, v1
	global_atomic_add_x2 v[168:169], v[0:1], off
	s_branch .LBB0_2754
.Lsp_hi:
	s_movk_i32 s39, 0x4000
	s_cmp_eq_u32 s100, 0x180
	s_cselect_b32 s39, 0x2000, s39
	s_cmp_eq_u32 s100, 0xc0
	s_cselect_b32 s39, 0, s39
	v_mov_b32_e32 v36, s39
	v_mov_b32_e32 v37, 0
	v_lshl_add_u64 v[34:35], v[34:35], 0, v[36:37]
	ds_read_b32 v40, v205
	v_add_u32_e32 v42, v70, v208
	ds_read_b32 v42, v42
	v_mov_b32_e32 v41, s38
	v_mov_b32_e32 v43, s38
	s_waitcnt lgkmcnt(0)
	global_store_dwordx2 v[34:35], v[40:41], off sc1
	global_store_dwordx2 v[34:35], v[42:43], off offset:8 sc1
	s_mov_b64 s[2:3], exec
	s_branch .LBB0_2754

.LBB0_2908:
	s_and_b64 vcc, exec, s[2:3]
	s_cbranch_vccz .LBB0_2985
	v_lshlrev_b32_e32 v0, 4, v26
	s_waitcnt lgkmcnt(0)
	v_add_u32_e32 v1, 0x2000, v0
	v_ashrrev_i32_e32 v2, 31, v1
	v_lshrrev_b32_e32 v2, 22, v2
	v_add_u32_e32 v2, v1, v2
	v_ashrrev_i32_e32 v28, 10, v2
	v_mul_i32_i24_e32 v2, 0x400, v28
	v_sub_u32_e32 v1, v1, v2
	v_lshrrev_b32_e32 v2, 4, v1
	v_bitop3_b32 v1, v2, v1, 32 bitop3:0x6c
	v_ashrrev_i32_e32 v2, 31, v1
	v_lshrrev_b32_e32 v2, 26, v2
	v_add_u32_e32 v2, v1, v2
	v_lshlrev_b32_e32 v3, 3, v28
	v_ashrrev_i32_e32 v29, 6, v2
	v_and_b32_e32 v3, -16, v3
	v_add_u32_e32 v3, v29, v3
	v_and_b32_e32 v4, 3, v29
	s_mov_b32 s1, 0xffffe0
	v_lshrrev_b32_e32 v5, 2, v3
	v_lshlrev_b32_e32 v6, 1, v3
	v_and_b32_e32 v2, 0xc0, v2
	v_and_or_b32 v4, v3, s1, v4
	v_and_b32_e32 v5, 4, v5
	v_and_b32_e32 v6, 24, v6
	v_sub_u32_e32 v1, v1, v2
	v_or3_b32 v4, v4, v5, v6
	v_lshlrev_b32_e32 v5, 5, v28
	v_ashrrev_i16_sdwa v1, v215, sext(v1) dst_sel:DWORD dst_unused:UNUSED_PAD src0_sel:DWORD src1_sel:BYTE_0
	v_and_b32_e32 v30, 32, v5
	v_bfe_i32 v31, v1, 0, 16
	s_movk_i32 s0, 0xb00
	v_mul_u32_u24_e32 v4, 0xb00, v4
	v_add_u32_e32 v1, v30, v31
	v_mul_lo_u32 v2, v3, s0
	v_add_lshl_u32 v130, v4, v1, 1
	v_add_lshl_u32 v132, v1, v2, 1
	v_bfe_i32 v1, v26, 27, 1
	v_lshrrev_b32_e32 v1, 22, v1
	v_add_u32_e32 v1, v0, v1
	v_and_b32_e32 v1, 0xfffffc00, v1
	v_sub_u32_e32 v0, v0, v1
	v_lshrrev_b32_e32 v1, 4, v0
	v_ashrrev_i32_e32 v2, 31, v26
	v_bitop3_b32 v0, v1, v0, 32 bitop3:0x6c
	v_lshrrev_b32_e32 v2, 26, v2
	v_ashrrev_i32_e32 v1, 31, v0
	v_add_u32_e32 v2, v26, v2
	v_lshrrev_b32_e32 v1, 26, v1
	v_ashrrev_i32_e32 v35, 6, v2
	v_add_u32_e32 v1, v0, v1
	v_lshlrev_b32_e32 v2, 3, v35
	v_ashrrev_i32_e32 v34, 6, v1
	v_and_b32_e32 v2, -16, v2
	v_add_u32_e32 v2, v34, v2
	v_and_b32_e32 v3, 3, v34
	v_lshrrev_b32_e32 v4, 2, v2
	v_lshlrev_b32_e32 v5, 1, v2
	v_and_b32_e32 v1, 0xc0, v1
	s_ashr_i32 s19, s8, 6
	v_and_or_b32 v3, v2, s1, v3
	v_and_b32_e32 v4, 4, v4
	v_and_b32_e32 v5, 24, v5
	v_sub_u32_e32 v0, v0, v1
	s_lshl_b32 s11, s19, 10
	v_or3_b32 v3, v3, v4, v5
	v_lshlrev_b32_e32 v4, 5, v35
	v_ashrrev_i16_sdwa v0, v215, sext(v0) dst_sel:DWORD dst_unused:UNUSED_PAD src0_sel:DWORD src1_sel:BYTE_0
	v_mul_lo_u32 v1, v2, s0
	v_readlane_b32 s0, v254, 19
	v_and_b32_e32 v36, 32, v4
	v_bfe_i32 v37, v0, 0, 16
	s_add_u32 s52, s77, s0
	v_readlane_b32 s0, v254, 17
	v_mul_u32_u24_e32 v3, 0xb00, v3
	v_add_u32_e32 v0, v36, v37
	s_addc_u32 s53, s78, s0
	s_add_i32 s12, s11, 0
	v_add_lshl_u32 v32, v3, v0, 1
	s_add_i32 m0, s12, 0x10000
	v_readlane_b32 s0, v254, 16
	global_load_lds_dwordx4 v32, s[52:53]
	s_add_i32 m0, s12, 0x12000
	s_add_u32 s2, s52, 0xb0000
	global_load_lds_dwordx4 v130, s[52:53]
	s_addc_u32 s3, s53, 0
	s_add_i32 m0, s12, 0x14000
	v_add_lshl_u32 v134, v0, v1, 1
	global_load_lds_dwordx4 v32, s[2:3]
	s_add_i32 m0, s12, 0x16000
	s_add_u32 s40, s75, s0
	v_readlane_b32 s0, v254, 13
	s_addc_u32 s41, s76, s0
	s_add_i32 s14, s12, 0x2000
	global_load_lds_dwordx4 v130, s[2:3]
	s_mov_b32 m0, s12
	s_add_u32 s2, s40, 0xb0000
	global_load_lds_dwordx4 v134, s[40:41]
	s_mov_b32 m0, s14
	s_addc_u32 s3, s41, 0
	s_add_i32 s15, s12, 0x4000
	global_load_lds_dwordx4 v132, s[40:41]
	s_mov_b32 m0, s15
	s_add_i32 s17, s12, 0x6000
	global_load_lds_dwordx4 v134, s[2:3]
	s_mov_b32 m0, s17
	v_and_b32_e32 v145, 64, v216
	global_load_lds_dwordx4 v132, s[2:3]
	s_ashr_i32 s2, s37, 31
	s_lshr_b32 s2, s2, 24
	s_add_i32 s2, s37, s2
	s_and_b32 s2, s2, 0xffffff00
	s_sub_i32 s13, s37, s2
	s_mov_b32 s100, 0
	s_mov_b32 s101, 0
	s_cmp_gt_i32 s13, 31
	v_xor_b32_e32 v144, 16, v216
	s_movk_i32 s0, 0x1ff
	s_cbranch_scc0 .Lsp2_go
	s_cmpk_lt_i32 s13, 0xa0
	s_cbranch_scc1 .LBB0_2933
	s_sub_i32 s101, s13, 0xa0
	s_lshr_b32 s101, s101, 5
	s_add_i32 s101, s101, 1
	s_mul_i32 s100, s101, 0xc0
	s_cmp_eq_u32 s101, 3
	s_cselect_b32 s101, 32, 0
	s_sub_i32 s100, s100, s101
	s_mov_b32 s101, 0
	s_and_b32 s13, s13, 31

.LBB0_2912:
	v_lshl_add_u64 v[248:249], v[162:163], 0, s[100:101]
	v_lshl_or_b32 v24, s13, 5, v201
	s_movk_i32 s1, 0x1600
	v_mad_i64_i32 v[60:61], s[2:3], v24, s1, v[164:165]
	v_lshl_add_u64 v[60:61], v[60:61], 0, s[100:101]
	global_load_dwordx4 v[64:67], v[248:249], off
	global_load_dwordx4 v[68:71], v[60:61], off
	global_load_dwordx4 v[72:75], v[248:249], off offset:32
	global_load_dwordx4 v[76:79], v[60:61], off offset:32
	global_load_dwordx4 v[80:83], v[248:249], off offset:64
	global_load_dwordx4 v[84:87], v[60:61], off offset:64
	global_load_dwordx4 v[88:91], v[248:249], off offset:96
	global_load_dwordx4 v[92:95], v[60:61], off offset:96
	global_load_dwordx4 v[96:99], v[248:249], off offset:128
	global_load_dwordx4 v[100:103], v[60:61], off offset:128
	global_load_dwordx4 v[104:107], v[248:249], off offset:160
	global_load_dwordx4 v[108:111], v[60:61], off offset:160
	v_add_u32_e32 v25, 0x8000, v204
	v_add_u32_e32 v44, v24, v202
	v_add_u32_e32 v46, 0x4000, v44
	v_ashrrev_i32_e32 v45, 31, v44
	v_ashrrev_i32_e32 v47, 31, v46
	v_lshl_add_u64 v[44:45], v[44:45], 2, s[92:93]
	v_lshl_add_u64 v[46:47], v[46:47], 2, s[92:93]
	global_load_dword v44, v[44:45], off
	s_nop 0
	global_load_dword v43, v[46:47], off
	v_add_u32_e32 v45, 0x8400, v204
	v_add_u32_e32 v46, 0x8800, v204
	v_add_u32_e32 v47, 0x8c00, v204
	s_waitcnt vmcnt(12)
	v_mfma_f32_32x32x16_bf16 v[0:15], v[64:67], v[68:71], 0
	s_waitcnt vmcnt(10)
	v_mfma_f32_32x32x16_bf16 v[0:15], v[72:75], v[76:79], v[0:15]
	s_waitcnt vmcnt(8)
	v_mfma_f32_32x32x16_bf16 v[0:15], v[80:83], v[84:87], v[0:15]
	s_waitcnt vmcnt(6)
	v_mfma_f32_32x32x16_bf16 v[0:15], v[88:91], v[92:95], v[0:15]
	s_waitcnt vmcnt(4)
	v_mfma_f32_32x32x16_bf16 v[0:15], v[96:99], v[100:103], v[0:15]
	s_cmp_lt_u32 s100, 0x180
	s_cbranch_scc0 .Lsp2_s6
	s_waitcnt vmcnt(2)
	v_mfma_f32_32x32x16_bf16 v[0:15], v[104:107], v[108:111], v[0:15]
.Lsp2_s6:
	s_waitcnt vmcnt(0)
	s_nop 11
	ds_write2_b32 v25, v0, v1 offset1:32
	ds_write2_b32 v25, v2, v3 offset0:64 offset1:96
	ds_write2_b32 v45, v4, v5 offset1:32
	ds_write2_b32 v45, v6, v7 offset0:64 offset1:96
	ds_write2_b32 v46, v8, v9 offset1:32
	ds_write2_b32 v46, v10, v11 offset0:64 offset1:96
	ds_write2_b32 v47, v12, v13 offset1:32
	ds_write2_b32 v47, v14, v15 offset0:64 offset1:96
	s_waitcnt lgkmcnt(0)
	s_barrier
	s_and_saveexec_b64 s[54:55], s[34:35]
	s_movk_i32 s1, 0x1080
	s_cbranch_execz .LBB0_2915
	s_mov_b64 s[2:3], 0
	v_mov_b32_e32 v0, v200

.LBB0_2915:
	s_or_b64 exec, exec, s[54:55]
	s_waitcnt lgkmcnt(0)
	s_barrier
	s_sub_u32 s54, s92, 0x24ac0000
	s_subb_u32 s55, s93, 0
	v_lshlrev_b32_e32 v48, 4, v200
	v_mov_b32_e32 v49, s13
	v_mul_u32_u24_e32 v49, 0x6000, v49
	v_add_u32_e32 v48, v48, v49
	v_mov_b32_e32 v49, 0
	v_lshl_add_u64 v[48:49], v[48:49], 0, s[54:55]
	v_readlane_b32 s54, v254, 49
	s_nop 3
	s_add_i32 s54, s54, 1
	s_cmp_lg_u32 s100, 0
	s_cbranch_scc1 .Lsp2_hi
	v_add_co_u32_e32 v50, vcc, 0x2000, v48
	v_addc_co_u32_e32 v51, vcc, 0, v49, vcc
	v_add_co_u32_e32 v52, vcc, 0x4000, v48
	v_addc_co_u32_e32 v53, vcc, 0, v49, vcc
	s_mov_b32 s55, 0
.Lsp2_poll:
	global_load_dwordx2 v[54:55], v[48:49], off sc1
	global_load_dwordx2 v[56:57], v[48:49], off offset:8 sc1
	global_load_dwordx2 v[58:59], v[50:51], off sc1
	global_load_dwordx2 v[16:17], v[50:51], off offset:8 sc1
	global_load_dwordx2 v[18:19], v[52:53], off sc1
	global_load_dwordx2 v[20:21], v[52:53], off offset:8 sc1
	s_waitcnt vmcnt(0)
	v_cmp_ne_u32_e32 vcc, s54, v55
	v_cmp_ne_u32_e64 s[2:3], s54, v57
	s_or_b64 vcc, vcc, s[2:3]
	v_cmp_ne_u32_e64 s[2:3], s54, v59
	s_or_b64 vcc, vcc, s[2:3]
	v_cmp_ne_u32_e64 s[2:3], s54, v17
	s_or_b64 vcc, vcc, s[2:3]
	v_cmp_ne_u32_e64 s[2:3], s54, v19
	s_or_b64 vcc, vcc, s[2:3]
	v_cmp_ne_u32_e64 s[2:3], s54, v21
	s_or_b64 vcc, vcc, s[2:3]
	s_cbranch_vccz .Lsp2_got
	s_add_i32 s55, s55, 1
	s_cmp_lt_u32 s55, 0x4000
	s_cbranch_scc0 .Lsp2_got
	s_sleep 2
	s_branch .Lsp2_poll
.Lsp2_got:
	ds_read_b32 v0, v205
	v_ashrrev_i32_e32 v25, 31, v24
	s_waitcnt vmcnt(1) lgkmcnt(0)
	v_add_f32_e32 v0, v0, v54
	v_add_f32_e32 v0, v0, v58
	v_add_f32_e32 v0, v0, v18
	v_add_f32_e32 v1, v44, v0
	v_mul_f32_e32 v0, v1, v1
	ds_bpermute_b32 v0, v38, v0
	s_waitcnt lgkmcnt(0)
	v_fmac_f32_e32 v0, v1, v1
	s_waitcnt lgkmcnt(0)
	s_nop 1
	v_add_f32_dpp v0, v0, v0 quad_perm:[2,3,0,1] row_mask:0xf bank_mask:0xf
	s_waitcnt lgkmcnt(0)
	s_nop 1
	v_add_f32_dpp v0, v0, v0 row_half_mirror row_mask:0xf bank_mask:0xf
	s_waitcnt lgkmcnt(0)
	s_nop 1
	v_add_f32_dpp v0, v0, v0 row_mirror row_mask:0xf bank_mask:0xf
	v_mov_b32_e32 v2, v0
	s_nop 1
	v_permlane16_swap_b32_e32 v2, v0
	s_and_saveexec_b64 s[2:3], s[90:91]
	s_cbranch_execz .LBB0_2917
	s_waitcnt lgkmcnt(0)
	v_add_f32_e32 v0, v0, v2
	v_mul_f32_e32 v0, 0x4b800000, v0
	v_trunc_f32_e32 v0, v0
	v_mul_f32_e32 v2, 0x2f800000, v0
	v_floor_f32_e32 v3, v2
	v_fmac_f32_e32 v0, 0xcf800000, v3
	v_cvt_u32_f32_e32 v2, v0
	v_cvt_u32_f32_e32 v3, v3
	global_atomic_add_x2 v[166:167], v[2:3], off
.LBB0_2917:
	s_or_b64 exec, exec, s[2:3]
	ds_read_b32 v0, v27
	s_waitcnt vmcnt(0) lgkmcnt(0)
	v_add_f32_e32 v0, v0, v56
	v_add_f32_e32 v0, v0, v16
	v_add_f32_e32 v0, v0, v20
	v_add_f32_e32 v0, v43, v0
	v_mul_f32_e32 v2, v0, v0
	ds_bpermute_b32 v2, v38, v2
	s_waitcnt lgkmcnt(0)
	v_fmac_f32_e32 v2, v0, v0
	s_waitcnt lgkmcnt(0)
	s_nop 1
	v_add_f32_dpp v2, v2, v2 quad_perm:[2,3,0,1] row_mask:0xf bank_mask:0xf
	s_waitcnt lgkmcnt(0)
	s_nop 1
	v_add_f32_dpp v2, v2, v2 row_half_mirror row_mask:0xf bank_mask:0xf
	s_waitcnt lgkmcnt(0)
	s_nop 1
	v_add_f32_dpp v2, v2, v2 row_mirror row_mask:0xf bank_mask:0xf
	v_mov_b32_e32 v3, v2
	s_nop 1
	v_permlane16_swap_b32_e32 v3, v2
	s_and_saveexec_b64 s[2:3], s[90:91]
	s_cbranch_execz .LBB0_2919
	s_waitcnt lgkmcnt(0)
	v_add_f32_e32 v2, v2, v3
	v_mul_f32_e32 v2, 0x4b800000, v2
	v_trunc_f32_e32 v2, v2
	v_mul_f32_e32 v3, 0x2f800000, v2
	v_floor_f32_e32 v3, v3
	v_fmac_f32_e32 v2, 0xcf800000, v3
	v_cvt_u32_f32_e32 v2, v2
	v_cvt_u32_f32_e32 v3, v3
	global_atomic_add_x2 v[168:169], v[2:3], off

.Lsp2_hi:
	s_movk_i32 s55, 0x4000
	s_cmp_eq_u32 s100, 0x180
	s_cselect_b32 s55, 0x2000, s55
	s_cmp_eq_u32 s100, 0xc0
	s_cselect_b32 s55, 0, s55
	v_mov_b32_e32 v50, s55
	v_mov_b32_e32 v51, 0
	v_lshl_add_u64 v[48:49], v[48:49], 0, v[50:51]
	ds_read_b32 v54, v205
	ds_read_b32 v56, v27
	v_mov_b32_e32 v55, s54
	v_mov_b32_e32 v57, s54
	s_waitcnt lgkmcnt(0)
	global_store_dwordx2 v[48:49], v[54:55], off sc1
	global_store_dwordx2 v[48:49], v[56:57], off offset:8 sc1
	s_branch .LBB0_2933
